# RESID epilogue half-wave row sums: xor 8/4/2/1 steps done with DPP adds instead of ds_bpermute round trips
# speedup vs baseline: 1.1264x; 1.0032x over previous
; DI void ssq_add(u64* p, float part) { atomicAdd(p, (u64)(part * 1048576.f + 0.5f)); }
; DI float hsum32(float v) {
; #pragma unroll
;   for (int o = 16; o > 0; o >>= 1) v += __shfl_xor(v, o);
;   return v;
; }
; DI void gemm_tile(const GemmDesc& d, int m0, int n0, bf16_t* smem, int dry) {
;     ...
;   if (d.epi == EPI_RESID) {
; #pragma unroll
;     for (int pass = 0; pass < 16; ++pass) {
;       const int row = pass * 8 + (t >> 5), c4 = t & 31, m = m0 + row;
;       float part = 0.f;
;       if (m < M) {
;         const f32x4 v = *(const f32x4*)(Ct + row * CS + c4 * 4);
;         const int n = d.c_off + n0 + c4 * 4;
;         f32x4 hv;
;         hv[0] = __uint_as_float(hpre[pass][0] << 16); hv[1] = __uint_as_float(hpre[pass][0] & 0xffff0000u);
;         hv[2] = __uint_as_float(hpre[pass][1] << 16); hv[3] = __uint_as_float(hpre[pass][1] & 0xffff0000u);
; #pragma unroll
;         for (int j = 0; j < 4; ++j) { hv[j] += v[j]; part += hv[j] * hv[j]; }
;         u32x2 o; o[0] = pk_bf16(hv[0], hv[1]); o[1] = pk_bf16(hv[2], hv[3]);
;         *(u32x2*)(d.hb + (size_t)m * D + n) = o;
;       }
;       part = hsum32(part);
;       if (c4 == 0 && m < M) ssq_add(d.ssq_out + m, part);
;     }
.LBB0_508:
	s_or_b64 exec, exec, s[6:7]
	ds_bpermute_b32 v11, v3, v10
	s_and_b64 s[6:7], vcc, s[4:5]
	s_waitcnt lgkmcnt(0)
	v_add_f32_e32 v10, v10, v11
	s_nop 1
	v_add_f32_dpp v10, v10, v10 row_ror:8 row_mask:0xf bank_mask:0xf
	s_nop 1
	v_add_f32_dpp v10, v10, v10 row_half_mirror row_mask:0xf bank_mask:0xf
	s_nop 1
	v_add_f32_dpp v10, v10, v10 quad_perm:[1,0,3,2] row_mask:0xf bank_mask:0xf
	s_nop 1
	v_add_f32_dpp v10, v10, v10 quad_perm:[2,3,0,1] row_mask:0xf bank_mask:0xf
	s_and_saveexec_b64 s[4:5], s[6:7]
	s_cbranch_execz .LBB0_510
	v_fma_f32 v10, v10, s2, 0.5
	v_trunc_f32_e32 v10, v10
	v_mul_f32_e32 v11, 0x2f800000, v10
	v_floor_f32_e32 v11, v11
	v_fmac_f32_e32 v10, 0xcf800000, v11
	v_cvt_u32_f32_e32 v10, v10
	v_cvt_u32_f32_e32 v11, v11
	v_lshl_add_u64 v[4:5], v[4:5], 3, s[14:15]
	global_atomic_add_x2 v[4:5], v[10:11], off

; DI void ssq_add(u64* p, float part) { atomicAdd(p, (u64)(part * 1048576.f + 0.5f)); }
; DI float hsum32(float v) {
; #pragma unroll
;   for (int o = 16; o > 0; o >>= 1) v += __shfl_xor(v, o);
;   return v;
; }
; DI void gemm_tile(const GemmDesc& d, int m0, int n0, bf16_t* smem, int dry) {
;     ...
;   if (d.epi == EPI_RESID) {
; #pragma unroll
;     for (int pass = 0; pass < 16; ++pass) {
;       const int row = pass * 8 + (t >> 5), c4 = t & 31, m = m0 + row;
;       float part = 0.f;
;       if (m < M) {
;         const f32x4 v = *(const f32x4*)(Ct + row * CS + c4 * 4);
;         const int n = d.c_off + n0 + c4 * 4;
;         f32x4 hv;
;         hv[0] = __uint_as_float(hpre[pass][0] << 16); hv[1] = __uint_as_float(hpre[pass][0] & 0xffff0000u);
;         hv[2] = __uint_as_float(hpre[pass][1] << 16); hv[3] = __uint_as_float(hpre[pass][1] & 0xffff0000u);
; #pragma unroll
;         for (int j = 0; j < 4; ++j) { hv[j] += v[j]; part += hv[j] * hv[j]; }
;         u32x2 o; o[0] = pk_bf16(hv[0], hv[1]); o[1] = pk_bf16(hv[2], hv[3]);
;         *(u32x2*)(d.hb + (size_t)m * D + n) = o;
;       }
;       part = hsum32(part);
;       if (c4 == 0 && m < M) ssq_add(d.ssq_out + m, part);
;     }
.LBB0_1535:
	s_or_b64 exec, exec, s[10:11]
	ds_bpermute_b32 v11, v3, v10
	s_and_b64 s[10:11], vcc, s[4:5]
	s_waitcnt lgkmcnt(0)
	v_add_f32_e32 v10, v10, v11
	s_nop 1
	v_add_f32_dpp v10, v10, v10 row_ror:8 row_mask:0xf bank_mask:0xf
	s_nop 1
	v_add_f32_dpp v10, v10, v10 row_half_mirror row_mask:0xf bank_mask:0xf
	s_nop 1
	v_add_f32_dpp v10, v10, v10 quad_perm:[1,0,3,2] row_mask:0xf bank_mask:0xf
	s_nop 1
	v_add_f32_dpp v10, v10, v10 quad_perm:[2,3,0,1] row_mask:0xf bank_mask:0xf
	s_and_saveexec_b64 s[4:5], s[10:11]
	s_cbranch_execz .LBB0_1537
	v_fma_f32 v10, v10, s2, 0.5
	v_trunc_f32_e32 v10, v10
	v_mul_f32_e32 v11, 0x2f800000, v10
	v_floor_f32_e32 v11, v11
	v_fmac_f32_e32 v10, 0xcf800000, v11
	v_cvt_u32_f32_e32 v10, v10
	v_cvt_u32_f32_e32 v11, v11
	v_lshl_add_u64 v[4:5], v[4:5], 3, s[8:9]
	global_atomic_add_x2 v[4:5], v[10:11], off
